# fin phase: 16-lane row reductions with DPP adds (quad_perm / row_half_mirror / row_mirror) instead of ds_bpermute
# speedup vs baseline: 1.0091x; 1.0022x over previous
.LBB0_80:
	v_add_u32_e32 v7, -7, v83
	v_mov_b64_e32 v[8:9], s[34:35]
	v_mad_i64_i32 v[10:11], s[0:1], v7, s9, v[8:9]
	v_mov_b32_e32 v7, v0
	v_lshl_add_u64 v[10:11], v[10:11], 0, v[6:7]
	v_add_co_u32_e32 v36, vcc, 0x1000, v10
	v_add_u32_e32 v10, -6, v83
	s_nop 0
	v_addc_co_u32_e32 v37, vcc, 0, v11, vcc
	global_load_dwordx2 v[70:71], v[36:37], off offset:512
	global_load_dwordx2 v[66:67], v[36:37], off offset:1024
	global_load_dwordx2 v[68:69], v[36:37], off offset:1568
	v_mad_i64_i32 v[10:11], s[0:1], v10, s9, v[8:9]
	v_lshl_add_u64 v[10:11], v[10:11], 0, v[6:7]
	v_add_co_u32_e32 v44, vcc, 0x1000, v10
	v_add_u32_e32 v10, -5, v83
	s_nop 0
	v_addc_co_u32_e32 v45, vcc, 0, v11, vcc
	global_load_dwordx2 v[76:77], v[44:45], off offset:512
	global_load_dwordx2 v[72:73], v[44:45], off offset:1024
	global_load_dwordx2 v[50:51], v[44:45], off offset:1568
	v_mad_i64_i32 v[10:11], s[0:1], v10, s9, v[8:9]
	v_lshl_add_u64 v[10:11], v[10:11], 0, v[6:7]
	v_add_co_u32_e32 v22, vcc, 0x1000, v10
	v_add_u32_e32 v10, -4, v83
	s_nop 0
	v_addc_co_u32_e32 v23, vcc, 0, v11, vcc
	v_mad_i64_i32 v[10:11], s[0:1], v10, s9, v[8:9]
	v_lshl_add_u64 v[10:11], v[10:11], 0, v[6:7]
	v_add_co_u32_e32 v32, vcc, 0x1000, v10
	v_add_u32_e32 v10, -3, v83
	s_nop 0
	v_addc_co_u32_e32 v33, vcc, 0, v11, vcc
	v_mad_i64_i32 v[10:11], s[0:1], v10, s9, v[8:9]
	v_lshl_add_u64 v[10:11], v[10:11], 0, v[6:7]
	v_add_co_u32_e32 v14, vcc, 0x1000, v10
	v_add_u32_e32 v10, -2, v83
	s_nop 0
	v_addc_co_u32_e32 v15, vcc, 0, v11, vcc
	v_mad_i64_i32 v[10:11], s[0:1], v10, s9, v[8:9]
	v_lshl_add_u64 v[10:11], v[10:11], 0, v[6:7]
	v_add_co_u32_e32 v16, vcc, 0x1000, v10
	v_add_u32_e32 v10, -1, v83
	s_nop 0
	v_addc_co_u32_e32 v17, vcc, 0, v11, vcc
	v_mad_i64_i32 v[10:11], s[0:1], v10, s9, v[8:9]
	v_mad_i64_i32 v[8:9], s[0:1], v83, s9, v[8:9]
	v_lshl_add_u64 v[10:11], v[10:11], 0, v[6:7]
	v_lshl_add_u64 v[8:9], v[8:9], 0, v[6:7]
	global_load_dwordx2 v[56:57], v[22:23], off offset:512
	global_load_dwordx2 v[54:55], v[22:23], off offset:1024
	global_load_dwordx2 v[52:53], v[22:23], off offset:1568
	global_load_dwordx2 v[60:61], v[32:33], off offset:512
	global_load_dwordx2 v[58:59], v[32:33], off offset:1024
	global_load_dwordx2 v[34:35], v[32:33], off offset:1568
	v_add_co_u32_e32 v10, vcc, 0x1000, v10
	global_load_dwordx2 v[42:43], v[14:15], off offset:512
	global_load_dwordx2 v[40:41], v[14:15], off offset:1024
	global_load_dwordx2 v[38:39], v[14:15], off offset:1568
	v_addc_co_u32_e32 v11, vcc, 0, v11, vcc
	v_add_co_u32_e32 v8, vcc, 0x1000, v8
	global_load_dwordx2 v[48:49], v[16:17], off offset:512
	global_load_dwordx2 v[46:47], v[16:17], off offset:1024
	global_load_dwordx2 v[24:25], v[16:17], off offset:1568
	v_addc_co_u32_e32 v9, vcc, 0, v9, vcc
	global_load_dwordx2 v[30:31], v[10:11], off offset:512
	global_load_dwordx2 v[28:29], v[10:11], off offset:1024
	global_load_dwordx2 v[26:27], v[10:11], off offset:1568
	global_load_dwordx2 v[20:21], v[8:9], off offset:512
	global_load_dwordx2 v[18:19], v[8:9], off offset:1024
	global_load_dwordx2 v[12:13], v[8:9], off offset:1568
	s_add_i32 s11, s11, s2
	v_add_u32_e32 v83, s10, v83
	s_cmpk_gt_i32 s11, 0x4ff
	s_waitcnt vmcnt(0)
	v_and_b32_e32 v63, 0xffff0000, v70
	v_lshlrev_b32_e32 v62, 16, v70
	v_and_b32_e32 v65, 0xffff0000, v66
	v_lshlrev_b32_e32 v64, 16, v66
	v_pk_add_f32 v[62:63], v[62:63], v[64:65]
	v_lshlrev_b32_e32 v64, 16, v68
	v_mul_f32_e32 v7, 0xbfb8aa3b, v64
	v_exp_f32_e32 v7, v7
	v_and_b32_e32 v65, 0xffff0000, v68
	v_lshlrev_b32_e32 v70, 16, v67
	v_pk_mul_f32 v[78:79], v[62:63], v[62:63]
	v_add_f32_e32 v7, 1.0, v7
	v_rcp_f32_e32 v74, v7
	v_mul_f32_e32 v7, 0xbfb8aa3b, v65
	v_exp_f32_e32 v7, v7
	s_nop 0
	v_add_f32_e32 v7, 1.0, v7
	v_rcp_f32_e32 v75, v7
	s_nop 0
	v_pk_mul_f32 v[64:65], v[74:75], v[64:65]
	v_and_b32_e32 v75, 0xffff0000, v71
	v_lshlrev_b32_e32 v74, 16, v71
	v_and_b32_e32 v71, 0xffff0000, v67
	v_pk_add_f32 v[66:67], v[74:75], v[70:71]
	v_lshlrev_b32_e32 v70, 16, v69
	v_mul_f32_e32 v7, 0xbfb8aa3b, v70
	v_exp_f32_e32 v7, v7
	v_and_b32_e32 v71, 0xffff0000, v69
	v_and_b32_e32 v75, 0xffff0000, v72
	v_lshlrev_b32_e32 v74, 16, v72
	v_add_f32_e32 v7, 1.0, v7
	v_rcp_f32_e32 v68, v7
	v_mul_f32_e32 v7, 0xbfb8aa3b, v71
	v_exp_f32_e32 v7, v7
	v_pk_mul_f32 v[84:85], v[66:67], v[66:67]
	v_add_f32_e32 v7, 1.0, v7
	v_rcp_f32_e32 v69, v7
	s_nop 0
	v_pk_mul_f32 v[70:71], v[68:69], v[70:71]
	v_and_b32_e32 v69, 0xffff0000, v76
	v_lshlrev_b32_e32 v68, 16, v76
	v_pk_add_f32 v[68:69], v[68:69], v[74:75]
	v_lshlrev_b32_e32 v74, 16, v50
	v_mul_f32_e32 v7, 0xbfb8aa3b, v74
	v_exp_f32_e32 v7, v7
	v_and_b32_e32 v75, 0xffff0000, v50
	v_lshlrev_b32_e32 v76, 16, v73
	v_pk_mul_f32 v[86:87], v[68:69], v[68:69]
	v_add_f32_e32 v7, 1.0, v7
	v_rcp_f32_e32 v88, v7
	v_mul_f32_e32 v7, 0xbfb8aa3b, v75
	v_exp_f32_e32 v7, v7
	s_nop 0
	v_add_f32_e32 v7, 1.0, v7
	v_rcp_f32_e32 v89, v7
	s_nop 0
	v_pk_mul_f32 v[74:75], v[88:89], v[74:75]
	v_and_b32_e32 v89, 0xffff0000, v77
	v_lshlrev_b32_e32 v88, 16, v77
	v_and_b32_e32 v77, 0xffff0000, v73
	v_pk_add_f32 v[72:73], v[88:89], v[76:77]
	v_mov_b32_e32 v88, v86
	v_pk_mul_f32 v[76:77], v[72:73], v[72:73]
	v_mov_b32_e32 v89, v78
	v_mov_b32_e32 v78, v87
	v_pk_add_f32 v[78:79], v[88:89], v[78:79]
	v_mov_b32_e32 v86, v76
	v_mov_b32_e32 v87, v84
	v_pk_add_f32 v[78:79], v[86:87], v[78:79]
	v_mov_b32_e32 v84, v77
	v_pk_add_f32 v[76:77], v[84:85], v[78:79]
	s_nop 1
	v_add_f32_dpp v76, v76, v76 quad_perm:[1,0,3,2] row_mask:0xf bank_mask:0xf
	v_add_f32_dpp v77, v77, v77 quad_perm:[1,0,3,2] row_mask:0xf bank_mask:0xf
	s_nop 0
	v_add_f32_dpp v76, v76, v76 quad_perm:[2,3,0,1] row_mask:0xf bank_mask:0xf
	v_add_f32_dpp v77, v77, v77 quad_perm:[2,3,0,1] row_mask:0xf bank_mask:0xf
	s_nop 0
	v_add_f32_dpp v76, v76, v76 row_half_mirror row_mask:0xf bank_mask:0xf
	v_add_f32_dpp v77, v77, v77 row_half_mirror row_mask:0xf bank_mask:0xf
	s_nop 0
	v_add_f32_dpp v76, v76, v76 row_mirror row_mask:0xf bank_mask:0xf
	v_add_f32_dpp v77, v77, v77 row_mirror row_mask:0xf bank_mask:0xf
	v_mov_b64_e32 v[78:79], s[40:41]
	v_pk_fma_f32 v[76:77], v[76:77], s[42:43], v[78:79] op_sel_hi:[1,0,0]
	s_nop 0
	v_mul_f32_e32 v7, 0x4b800000, v77
	v_cmp_gt_f32_e64 s[0:1], s12, v77
	v_cmp_gt_f32_e32 vcc, s12, v76
	s_nop 0
	v_cndmask_b32_e64 v7, v77, v7, s[0:1]
	v_rsq_f32_e32 v7, v7
	s_nop 0
	v_mul_f32_e32 v50, 0x45800000, v7
	v_cndmask_b32_e64 v50, v7, v50, s[0:1]
	v_pk_mul_f32 v[62:63], v[62:63], v[50:51] op_sel_hi:[1,0]
	v_mul_f32_e32 v7, 0x4b800000, v76
	v_pk_mul_f32 v[62:63], v[2:3], v[62:63]
	v_cndmask_b32_e32 v7, v76, v7, vcc
	v_pk_mul_f32 v[62:63], v[64:65], v[62:63]
	v_pk_mul_f32 v[64:65], v[66:67], v[50:51] op_sel_hi:[1,0]
	v_rsq_f32_e32 v7, v7
	v_pk_mul_f32 v[64:65], v[4:5], v[64:65]
	v_cvt_pk_bf16_f32 v62, v62, v63
	v_pk_mul_f32 v[64:65], v[70:71], v[64:65]
	v_lshlrev_b32_e32 v66, 16, v34
	v_cvt_pk_bf16_f32 v63, v64, v65
	global_store_dwordx2 v[36:37], v[62:63], off
	v_mul_f32_e32 v36, 0x45800000, v7
	v_cndmask_b32_e32 v36, v7, v36, vcc
	v_pk_mul_f32 v[62:63], v[68:69], v[36:37] op_sel_hi:[1,0]
	v_pk_mul_f32 v[36:37], v[72:73], v[36:37] op_sel_hi:[1,0]
	v_pk_mul_f32 v[62:63], v[2:3], v[62:63]
	v_pk_mul_f32 v[36:37], v[4:5], v[36:37]
	v_pk_mul_f32 v[62:63], v[74:75], v[62:63]
	v_and_b32_e32 v67, 0xffff0000, v34
	v_cvt_pk_bf16_f32 v50, v62, v63
	v_lshlrev_b32_e32 v62, 16, v51
	v_mul_f32_e32 v7, 0xbfb8aa3b, v62
	v_exp_f32_e32 v7, v7
	v_and_b32_e32 v63, 0xffff0000, v51
	v_add_f32_e32 v7, 1.0, v7
	v_rcp_f32_e32 v64, v7
	v_mul_f32_e32 v7, 0xbfb8aa3b, v63
	v_exp_f32_e32 v7, v7
	s_nop 0
	v_add_f32_e32 v7, 1.0, v7
	v_rcp_f32_e32 v65, v7
	s_nop 0
	v_pk_mul_f32 v[62:63], v[64:65], v[62:63]
	s_nop 0
	v_pk_mul_f32 v[36:37], v[62:63], v[36:37]
	v_and_b32_e32 v65, 0xffff0000, v58
	v_cvt_pk_bf16_f32 v51, v36, v37
	global_store_dwordx2 v[44:45], v[50:51], off
	v_lshlrev_b32_e32 v50, 16, v52
	v_mul_f32_e32 v7, 0xbfb8aa3b, v50
	v_exp_f32_e32 v7, v7
	v_and_b32_e32 v51, 0xffff0000, v52
	v_and_b32_e32 v37, 0xffff0000, v56
	v_lshlrev_b32_e32 v36, 16, v56
	v_add_f32_e32 v7, 1.0, v7
	v_rcp_f32_e32 v62, v7
	v_mul_f32_e32 v7, 0xbfb8aa3b, v51
	v_exp_f32_e32 v7, v7
	v_lshlrev_b32_e32 v56, 16, v55
	v_and_b32_e32 v45, 0xffff0000, v54
	v_lshlrev_b32_e32 v44, 16, v54
	v_add_f32_e32 v7, 1.0, v7
	v_rcp_f32_e32 v63, v7
	v_lshlrev_b32_e32 v64, 16, v58
	v_pk_add_f32 v[36:37], v[36:37], v[44:45]
	v_pk_mul_f32 v[50:51], v[62:63], v[50:51]
	v_and_b32_e32 v63, 0xffff0000, v57
	v_lshlrev_b32_e32 v62, 16, v57
	v_and_b32_e32 v57, 0xffff0000, v55
	v_pk_add_f32 v[54:55], v[62:63], v[56:57]
	v_lshlrev_b32_e32 v62, 16, v53
	v_mul_f32_e32 v7, 0xbfb8aa3b, v62
	v_exp_f32_e32 v7, v7
	v_and_b32_e32 v63, 0xffff0000, v53
	v_pk_mul_f32 v[44:45], v[36:37], v[36:37]
	v_pk_mul_f32 v[56:57], v[54:55], v[54:55]
	v_add_f32_e32 v7, 1.0, v7
	v_rcp_f32_e32 v52, v7
	v_mul_f32_e32 v7, 0xbfb8aa3b, v63
	v_exp_f32_e32 v7, v7
	s_nop 0
	v_add_f32_e32 v7, 1.0, v7
	v_rcp_f32_e32 v53, v7
	v_mul_f32_e32 v7, 0xbfb8aa3b, v66
	v_exp_f32_e32 v7, v7
	v_pk_mul_f32 v[52:53], v[52:53], v[62:63]
	v_and_b32_e32 v63, 0xffff0000, v60
	v_add_f32_e32 v7, 1.0, v7
	v_rcp_f32_e32 v68, v7
	v_mul_f32_e32 v7, 0xbfb8aa3b, v67
	v_exp_f32_e32 v7, v7
	v_lshlrev_b32_e32 v62, 16, v60
	v_pk_add_f32 v[62:63], v[62:63], v[64:65]
	v_lshlrev_b32_e32 v60, 16, v59
	v_add_f32_e32 v7, 1.0, v7
	v_rcp_f32_e32 v69, v7
	v_pk_mul_f32 v[64:65], v[62:63], v[62:63]
	v_pk_mul_f32 v[66:67], v[68:69], v[66:67]
	v_and_b32_e32 v69, 0xffff0000, v61
	v_lshlrev_b32_e32 v68, 16, v61
	v_and_b32_e32 v61, 0xffff0000, v59
	v_pk_add_f32 v[58:59], v[68:69], v[60:61]
	v_mov_b32_e32 v68, v64
	v_pk_mul_f32 v[60:61], v[58:59], v[58:59]
	v_mov_b32_e32 v69, v44
	v_mov_b32_e32 v44, v65
	v_pk_add_f32 v[44:45], v[68:69], v[44:45]
	v_mov_b32_e32 v64, v60
	v_mov_b32_e32 v65, v56
	v_pk_add_f32 v[44:45], v[64:65], v[44:45]
	v_mov_b32_e32 v56, v61
	v_pk_add_f32 v[44:45], v[56:57], v[44:45]
	s_nop 1
	v_add_f32_dpp v44, v44, v44 quad_perm:[1,0,3,2] row_mask:0xf bank_mask:0xf
	v_add_f32_dpp v45, v45, v45 quad_perm:[1,0,3,2] row_mask:0xf bank_mask:0xf
	s_nop 0
	v_add_f32_dpp v44, v44, v44 quad_perm:[2,3,0,1] row_mask:0xf bank_mask:0xf
	v_add_f32_dpp v45, v45, v45 quad_perm:[2,3,0,1] row_mask:0xf bank_mask:0xf
	s_nop 0
	v_add_f32_dpp v44, v44, v44 row_half_mirror row_mask:0xf bank_mask:0xf
	v_add_f32_dpp v45, v45, v45 row_half_mirror row_mask:0xf bank_mask:0xf
	s_nop 0
	v_add_f32_dpp v44, v44, v44 row_mirror row_mask:0xf bank_mask:0xf
	v_add_f32_dpp v45, v45, v45 row_mirror row_mask:0xf bank_mask:0xf
	s_nop 0
	v_pk_fma_f32 v[44:45], v[44:45], s[42:43], v[78:79] op_sel_hi:[1,0,0]
	s_nop 0
	v_mul_f32_e32 v7, 0x4b800000, v45
	v_cmp_gt_f32_e64 s[0:1], s12, v45
	v_cmp_gt_f32_e32 vcc, s12, v44
	s_nop 0
	v_cndmask_b32_e64 v7, v45, v7, s[0:1]
	v_rsq_f32_e32 v7, v7
	s_nop 0
	v_mul_f32_e32 v34, 0x45800000, v7
	v_cndmask_b32_e64 v34, v7, v34, s[0:1]
	v_pk_mul_f32 v[36:37], v[36:37], v[34:35] op_sel_hi:[1,0]
	v_mul_f32_e32 v7, 0x4b800000, v44
	v_pk_mul_f32 v[36:37], v[2:3], v[36:37]
	v_cndmask_b32_e32 v7, v44, v7, vcc
	v_pk_mul_f32 v[36:37], v[50:51], v[36:37]
	v_pk_mul_f32 v[50:51], v[54:55], v[34:35] op_sel_hi:[1,0]
	v_rsq_f32_e32 v7, v7
	v_pk_mul_f32 v[50:51], v[4:5], v[50:51]
	v_cvt_pk_bf16_f32 v36, v36, v37
	v_pk_mul_f32 v[50:51], v[52:53], v[50:51]
	s_nop 0
	v_cvt_pk_bf16_f32 v37, v50, v51
	global_store_dwordx2 v[22:23], v[36:37], off
	v_mul_f32_e32 v22, 0x45800000, v7
	v_cndmask_b32_e32 v22, v7, v22, vcc
	v_pk_mul_f32 v[36:37], v[62:63], v[22:23] op_sel_hi:[1,0]
	v_pk_mul_f32 v[22:23], v[58:59], v[22:23] op_sel_hi:[1,0]
	v_pk_mul_f32 v[36:37], v[2:3], v[36:37]
	v_pk_mul_f32 v[22:23], v[4:5], v[22:23]
	v_pk_mul_f32 v[36:37], v[66:67], v[36:37]
	v_lshlrev_b32_e32 v50, 16, v24
	v_cvt_pk_bf16_f32 v34, v36, v37
	v_lshlrev_b32_e32 v36, 16, v35
	v_mul_f32_e32 v7, 0xbfb8aa3b, v36
	v_exp_f32_e32 v7, v7
	v_and_b32_e32 v37, 0xffff0000, v35
	v_and_b32_e32 v51, 0xffff0000, v24
	v_add_f32_e32 v7, 1.0, v7
	v_rcp_f32_e32 v44, v7
	v_mul_f32_e32 v7, 0xbfb8aa3b, v37
	v_exp_f32_e32 v7, v7
	s_nop 0
	v_add_f32_e32 v7, 1.0, v7
	v_rcp_f32_e32 v45, v7
	s_nop 0
	v_pk_mul_f32 v[36:37], v[44:45], v[36:37]
	s_nop 0
	v_pk_mul_f32 v[22:23], v[36:37], v[22:23]
	v_and_b32_e32 v45, 0xffff0000, v46
	v_cvt_pk_bf16_f32 v35, v22, v23
	global_store_dwordx2 v[32:33], v[34:35], off
	v_lshlrev_b32_e32 v34, 16, v38
	v_mul_f32_e32 v7, 0xbfb8aa3b, v34
	v_exp_f32_e32 v7, v7
	v_and_b32_e32 v35, 0xffff0000, v38
	v_and_b32_e32 v23, 0xffff0000, v42
	v_lshlrev_b32_e32 v22, 16, v42
	v_add_f32_e32 v7, 1.0, v7
	v_rcp_f32_e32 v36, v7
	v_mul_f32_e32 v7, 0xbfb8aa3b, v35
	v_exp_f32_e32 v7, v7
	v_lshlrev_b32_e32 v42, 16, v41
	v_and_b32_e32 v33, 0xffff0000, v40
	v_lshlrev_b32_e32 v32, 16, v40
	v_add_f32_e32 v7, 1.0, v7
	v_rcp_f32_e32 v37, v7
	v_lshlrev_b32_e32 v44, 16, v46
	v_pk_add_f32 v[22:23], v[22:23], v[32:33]
	v_pk_mul_f32 v[34:35], v[36:37], v[34:35]
	v_and_b32_e32 v37, 0xffff0000, v43
	v_lshlrev_b32_e32 v36, 16, v43
	v_and_b32_e32 v43, 0xffff0000, v41
	v_pk_add_f32 v[36:37], v[36:37], v[42:43]
	v_lshlrev_b32_e32 v42, 16, v39
	v_mul_f32_e32 v7, 0xbfb8aa3b, v42
	v_exp_f32_e32 v7, v7
	v_and_b32_e32 v43, 0xffff0000, v39
	v_pk_mul_f32 v[32:33], v[22:23], v[22:23]
	v_pk_mul_f32 v[40:41], v[36:37], v[36:37]
	v_add_f32_e32 v7, 1.0, v7
	v_rcp_f32_e32 v38, v7
	v_mul_f32_e32 v7, 0xbfb8aa3b, v43
	v_exp_f32_e32 v7, v7
	s_nop 0
	v_add_f32_e32 v7, 1.0, v7
	v_rcp_f32_e32 v39, v7
	v_mul_f32_e32 v7, 0xbfb8aa3b, v50
	v_exp_f32_e32 v7, v7
	v_pk_mul_f32 v[38:39], v[38:39], v[42:43]
	v_and_b32_e32 v43, 0xffff0000, v48
	v_add_f32_e32 v7, 1.0, v7
	v_rcp_f32_e32 v52, v7
	v_mul_f32_e32 v7, 0xbfb8aa3b, v51
	v_exp_f32_e32 v7, v7
	v_lshlrev_b32_e32 v42, 16, v48
	v_pk_add_f32 v[42:43], v[42:43], v[44:45]
	v_lshlrev_b32_e32 v48, 16, v47
	v_add_f32_e32 v7, 1.0, v7
	v_rcp_f32_e32 v53, v7
	v_pk_mul_f32 v[44:45], v[42:43], v[42:43]
	v_pk_mul_f32 v[50:51], v[52:53], v[50:51]
	v_and_b32_e32 v53, 0xffff0000, v49
	v_lshlrev_b32_e32 v52, 16, v49
	v_and_b32_e32 v49, 0xffff0000, v47
	v_pk_add_f32 v[46:47], v[52:53], v[48:49]
	v_mov_b32_e32 v52, v44
	v_pk_mul_f32 v[48:49], v[46:47], v[46:47]
	v_mov_b32_e32 v53, v32
	v_mov_b32_e32 v32, v45
	v_pk_add_f32 v[32:33], v[52:53], v[32:33]
	v_mov_b32_e32 v44, v48
	v_mov_b32_e32 v45, v40
	v_pk_add_f32 v[32:33], v[44:45], v[32:33]
	v_mov_b32_e32 v40, v49
	v_pk_add_f32 v[32:33], v[40:41], v[32:33]
	s_nop 1
	v_add_f32_dpp v32, v32, v32 quad_perm:[1,0,3,2] row_mask:0xf bank_mask:0xf
	v_add_f32_dpp v33, v33, v33 quad_perm:[1,0,3,2] row_mask:0xf bank_mask:0xf
	s_nop 0
	v_add_f32_dpp v32, v32, v32 quad_perm:[2,3,0,1] row_mask:0xf bank_mask:0xf
	v_add_f32_dpp v33, v33, v33 quad_perm:[2,3,0,1] row_mask:0xf bank_mask:0xf
	s_nop 0
	v_add_f32_dpp v32, v32, v32 row_half_mirror row_mask:0xf bank_mask:0xf
	v_add_f32_dpp v33, v33, v33 row_half_mirror row_mask:0xf bank_mask:0xf
	s_nop 0
	v_add_f32_dpp v32, v32, v32 row_mirror row_mask:0xf bank_mask:0xf
	v_add_f32_dpp v33, v33, v33 row_mirror row_mask:0xf bank_mask:0xf
	s_nop 0
	v_pk_fma_f32 v[32:33], v[32:33], s[42:43], v[78:79] op_sel_hi:[1,0,0]
	s_nop 0
	v_mul_f32_e32 v7, 0x4b800000, v33
	v_cmp_gt_f32_e64 s[0:1], s12, v33
	v_cmp_gt_f32_e32 vcc, s12, v32
	s_nop 0
	v_cndmask_b32_e64 v7, v33, v7, s[0:1]
	v_rsq_f32_e32 v7, v7
	v_and_b32_e32 v33, 0xffff0000, v25
	v_mul_f32_e32 v24, 0x45800000, v7
	v_cndmask_b32_e64 v24, v7, v24, s[0:1]
	v_pk_mul_f32 v[22:23], v[22:23], v[24:25] op_sel_hi:[1,0]
	v_mul_f32_e32 v7, 0x4b800000, v32
	v_pk_mul_f32 v[22:23], v[2:3], v[22:23]
	v_cndmask_b32_e32 v7, v32, v7, vcc
	v_pk_mul_f32 v[22:23], v[34:35], v[22:23]
	v_pk_mul_f32 v[34:35], v[36:37], v[24:25] op_sel_hi:[1,0]
	v_rsq_f32_e32 v7, v7
	v_pk_mul_f32 v[34:35], v[4:5], v[34:35]
	v_cvt_pk_bf16_f32 v22, v22, v23
	v_pk_mul_f32 v[34:35], v[38:39], v[34:35]
	v_lshlrev_b32_e32 v32, 16, v25
	v_cvt_pk_bf16_f32 v23, v34, v35
	global_store_dwordx2 v[14:15], v[22:23], off
	v_mul_f32_e32 v14, 0x45800000, v7
	v_cndmask_b32_e32 v14, v7, v14, vcc
	v_mul_f32_e32 v7, 0xbfb8aa3b, v32
	v_exp_f32_e32 v7, v7
	v_pk_mul_f32 v[22:23], v[42:43], v[14:15] op_sel_hi:[1,0]
	v_pk_mul_f32 v[14:15], v[46:47], v[14:15] op_sel_hi:[1,0]
	v_pk_mul_f32 v[22:23], v[2:3], v[22:23]
	v_add_f32_e32 v7, 1.0, v7
	v_rcp_f32_e32 v24, v7
	v_mul_f32_e32 v7, 0xbfb8aa3b, v33
	v_exp_f32_e32 v7, v7
	v_pk_mul_f32 v[14:15], v[4:5], v[14:15]
	v_pk_mul_f32 v[22:23], v[50:51], v[22:23]
	v_lshlrev_b32_e32 v34, 16, v12
	v_add_f32_e32 v7, 1.0, v7
	v_rcp_f32_e32 v25, v7
	v_cvt_pk_bf16_f32 v22, v22, v23
	v_and_b32_e32 v35, 0xffff0000, v12
	v_pk_mul_f32 v[24:25], v[24:25], v[32:33]
	s_nop 0
	v_pk_mul_f32 v[14:15], v[24:25], v[14:15]
	v_and_b32_e32 v33, 0xffff0000, v18
	v_cvt_pk_bf16_f32 v23, v14, v15
	global_store_dwordx2 v[16:17], v[22:23], off
	v_lshlrev_b32_e32 v22, 16, v26
	v_mul_f32_e32 v7, 0xbfb8aa3b, v22
	v_exp_f32_e32 v7, v7
	v_and_b32_e32 v23, 0xffff0000, v26
	v_and_b32_e32 v15, 0xffff0000, v30
	v_lshlrev_b32_e32 v14, 16, v30
	v_add_f32_e32 v7, 1.0, v7
	v_rcp_f32_e32 v24, v7
	v_mul_f32_e32 v7, 0xbfb8aa3b, v23
	v_exp_f32_e32 v7, v7
	v_lshlrev_b32_e32 v30, 16, v29
	v_and_b32_e32 v17, 0xffff0000, v28
	v_lshlrev_b32_e32 v16, 16, v28
	v_add_f32_e32 v7, 1.0, v7
	v_rcp_f32_e32 v25, v7
	v_lshlrev_b32_e32 v32, 16, v18
	v_pk_add_f32 v[14:15], v[14:15], v[16:17]
	v_pk_mul_f32 v[22:23], v[24:25], v[22:23]
	v_and_b32_e32 v25, 0xffff0000, v31
	v_lshlrev_b32_e32 v24, 16, v31
	v_and_b32_e32 v31, 0xffff0000, v29
	v_pk_add_f32 v[24:25], v[24:25], v[30:31]
	v_lshlrev_b32_e32 v30, 16, v27
	v_mul_f32_e32 v7, 0xbfb8aa3b, v30
	v_exp_f32_e32 v7, v7
	v_and_b32_e32 v31, 0xffff0000, v27
	v_pk_mul_f32 v[16:17], v[14:15], v[14:15]
	v_pk_mul_f32 v[28:29], v[24:25], v[24:25]
	v_add_f32_e32 v7, 1.0, v7
	v_rcp_f32_e32 v26, v7
	v_mul_f32_e32 v7, 0xbfb8aa3b, v31
	v_exp_f32_e32 v7, v7
	s_nop 0
	v_add_f32_e32 v7, 1.0, v7
	v_rcp_f32_e32 v27, v7
	v_mul_f32_e32 v7, 0xbfb8aa3b, v34
	v_exp_f32_e32 v7, v7
	v_pk_mul_f32 v[26:27], v[26:27], v[30:31]
	v_and_b32_e32 v31, 0xffff0000, v20
	v_add_f32_e32 v7, 1.0, v7
	v_rcp_f32_e32 v36, v7
	v_mul_f32_e32 v7, 0xbfb8aa3b, v35
	v_exp_f32_e32 v7, v7
	v_lshlrev_b32_e32 v30, 16, v20
	v_pk_add_f32 v[30:31], v[30:31], v[32:33]
	v_lshlrev_b32_e32 v20, 16, v19
	v_add_f32_e32 v7, 1.0, v7
	v_rcp_f32_e32 v37, v7
	v_pk_mul_f32 v[32:33], v[30:31], v[30:31]
	v_pk_mul_f32 v[34:35], v[36:37], v[34:35]
	v_and_b32_e32 v37, 0xffff0000, v21
	v_lshlrev_b32_e32 v36, 16, v21
	v_and_b32_e32 v21, 0xffff0000, v19
	v_pk_add_f32 v[18:19], v[36:37], v[20:21]
	v_mov_b32_e32 v36, v32
	v_pk_mul_f32 v[20:21], v[18:19], v[18:19]
	v_mov_b32_e32 v37, v16
	v_mov_b32_e32 v16, v33
	v_pk_add_f32 v[16:17], v[36:37], v[16:17]
	v_mov_b32_e32 v32, v20
	v_mov_b32_e32 v33, v28
	v_pk_add_f32 v[16:17], v[32:33], v[16:17]
	v_mov_b32_e32 v28, v21
	v_pk_add_f32 v[16:17], v[28:29], v[16:17]
	s_nop 1
	v_add_f32_dpp v16, v16, v16 quad_perm:[1,0,3,2] row_mask:0xf bank_mask:0xf
	v_add_f32_dpp v17, v17, v17 quad_perm:[1,0,3,2] row_mask:0xf bank_mask:0xf
	s_nop 0
	v_add_f32_dpp v16, v16, v16 quad_perm:[2,3,0,1] row_mask:0xf bank_mask:0xf
	v_add_f32_dpp v17, v17, v17 quad_perm:[2,3,0,1] row_mask:0xf bank_mask:0xf
	s_nop 0
	v_add_f32_dpp v16, v16, v16 row_half_mirror row_mask:0xf bank_mask:0xf
	v_add_f32_dpp v17, v17, v17 row_half_mirror row_mask:0xf bank_mask:0xf
	s_nop 0
	v_add_f32_dpp v16, v16, v16 row_mirror row_mask:0xf bank_mask:0xf
	v_add_f32_dpp v17, v17, v17 row_mirror row_mask:0xf bank_mask:0xf
	s_nop 0
	v_pk_fma_f32 v[16:17], v[16:17], s[42:43], v[78:79] op_sel_hi:[1,0,0]
	s_nop 0
	v_mul_f32_e32 v7, 0x4b800000, v17
	v_cmp_gt_f32_e64 s[0:1], s12, v17
	v_cmp_gt_f32_e32 vcc, s12, v16
	s_nop 0
	v_cndmask_b32_e64 v7, v17, v7, s[0:1]
	v_rsq_f32_e32 v7, v7
	s_nop 0
	v_mul_f32_e32 v12, 0x45800000, v7
	v_cndmask_b32_e64 v12, v7, v12, s[0:1]
	v_mul_f32_e32 v7, 0x4b800000, v16
	v_cndmask_b32_e32 v7, v16, v7, vcc
	v_pk_mul_f32 v[14:15], v[14:15], v[12:13] op_sel_hi:[1,0]
	v_pk_mul_f32 v[20:21], v[24:25], v[12:13] op_sel_hi:[1,0]
	v_rsq_f32_e32 v7, v7
	v_pk_mul_f32 v[14:15], v[2:3], v[14:15]
	v_pk_mul_f32 v[20:21], v[4:5], v[20:21]
	v_pk_mul_f32 v[14:15], v[22:23], v[14:15]
	v_pk_mul_f32 v[20:21], v[26:27], v[20:21]
	v_cvt_pk_bf16_f32 v14, v14, v15
	v_cvt_pk_bf16_f32 v15, v20, v21
	global_store_dwordx2 v[10:11], v[14:15], off
	v_mul_f32_e32 v10, 0x45800000, v7
	v_cndmask_b32_e32 v10, v7, v10, vcc
	v_pk_mul_f32 v[14:15], v[30:31], v[10:11] op_sel_hi:[1,0]
	v_pk_mul_f32 v[10:11], v[18:19], v[10:11] op_sel_hi:[1,0]
	v_pk_mul_f32 v[14:15], v[2:3], v[14:15]
	v_pk_mul_f32 v[10:11], v[4:5], v[10:11]
	v_pk_mul_f32 v[14:15], v[34:35], v[14:15]
	s_nop 0
	v_cvt_pk_bf16_f32 v12, v14, v15
	v_lshlrev_b32_e32 v14, 16, v13
	v_mul_f32_e32 v7, 0xbfb8aa3b, v14
	v_exp_f32_e32 v7, v7
	v_and_b32_e32 v15, 0xffff0000, v13
	v_add_f32_e32 v7, 1.0, v7
	v_rcp_f32_e32 v16, v7
	v_mul_f32_e32 v7, 0xbfb8aa3b, v15
	v_exp_f32_e32 v7, v7
	s_nop 0
	v_add_f32_e32 v7, 1.0, v7
	v_rcp_f32_e32 v17, v7
	s_nop 0
	v_pk_mul_f32 v[14:15], v[16:17], v[14:15]
	s_nop 0
	v_pk_mul_f32 v[10:11], v[14:15], v[10:11]
	s_nop 0
	v_cvt_pk_bf16_f32 v13, v10, v11
	global_store_dwordx2 v[8:9], v[12:13], off
	s_cbranch_scc0 .LBB0_80
